# up K-loop: LDS-DMA loads use the SGPR-base + 32-bit VGPR offset form (no 64-bit VALU address adds), B-fragment ds_reads use one precomputed base with immediate offsets (no per-read VALU), plus C=0 fir
# speedup vs baseline: 1.0125x; 1.0125x over previous
; #define PG8_STAGE(bufoff, gbase, voff) do { _Pragma("unroll") for (int _i = 0; _i < 2; ++_i) \
;         __builtin_amdgcn_global_load_lds((const unsigned*)((const char*)(gbase) + (voff)[_i]), (PG8_LAS unsigned*)(lds + (bufoff) + ldsw + _i * 8192), 16, 0, 0); } while (0)
; #define PG8_LDA(dst, b, h) do { _Pragma("unroll") for (int m = 0; m < 4; ++m) _Pragma("unroll") for (int k = 0; k < 2; ++k) dst[m][k] = *(const PG8_LAS bf16x8*)(lds + PG8_SA(b, h) + aoff + m * 2048 + k * 1024); } while (0)
; #define PG8_LDB(dst, b, h) do { _Pragma("unroll") for (int n = 0; n < 2; ++n) _Pragma("unroll") for (int k = 0; k < 2; ++k) dst[n][k] = *(const PG8_LAS bf16x8*)(lds + PG8_SB(b, h) + boff + n * 2048 + k * 1024); } while (0)
; #define PG8_MMA(ai, bj, At, Bt) do { __builtin_amdgcn_s_setprio(1); _Pragma("unroll") for (int m = 0; m < 4; ++m) _Pragma("unroll") for (int n = 0; n < 2; ++n) _Pragma("unroll") for (int k = 0; k < 2; ++k) \
;         acc[ai][bj][m][n] = __builtin_amdgcn_mfma_f32_16x16x32_bf16(Bt[n][k], At[m][k], acc[ai][bj][m][n], 0, 0, 0); __builtin_amdgcn_s_setprio(0); } while (0)
; #define PG8_BAR __builtin_amdgcn_s_barrier()
; template <class Epi, class Sched, bool ALIGN_EPI = false, bool SP2 = false>
; __device__ __forceinline__ void gemm_phase(PG8_LAS unsigned char* lds, const Gemm g, const Sched& S, const Epi& E) {
;     ...
;         const bool has_next = S.next(ui + 1, nxt);
;         const char* nA = has_next ? (const char*)g.A + (size_t)nxt.pm * tstep : cA; const char* nB = has_next ? (const char*)g.Bt + (size_t)nxt.pn * tstep : cB;
;         for (int t = 0; t < nt; t += 2) {
;             const bool last = (t == nt - 2);
;             const char* a1 = cA + (size_t)(t + 1) * kstep;
;             const char* a2 = last ? nA : cA + (size_t)(t + 2) * kstep; const char* b2 = last ? nB : cB + (size_t)(t + 2) * kstep;
;             const char* a3 = a2 + kstep; const char* b3 = b2 + kstep;
;             if (last && has_next) S.a_ready(nxt);
;             if constexpr (SP2) {
;             PG8_LDB(B0, 0, 0); PG8_LDB(B1, 0, 1); PG8_SCHED; PG8_LDA(At, 0, 0); PG8_STAGE(PG8_SA(1, 1), a1 + hstep, voffA);
;             PG8_WAIT_V(8); PG8_WAIT_L(0); PG8_BAR; PG8_MMA(0, 0, At, B0); PG8_MMA(0, 1, At, B1); PG8_BAR; PG8_SCHED;
;             PG8_LDA(At, 0, 1); PG8_STAGE(PG8_SB(0, 0), b2, voffB); PG8_STAGE(PG8_SB(0, 1), b2 + hstep, voffB); PG8_STAGE(PG8_SA(0, 0), a2, voffA);
.LBB0_445:
	s_ashr_i32 s7, s6, 31
	s_lshl_b64 s[10:11], s[6:7], 19
	s_add_u32 s10, s23, s10
	s_addc_u32 s11, s24, s11
	s_and_b64 s[12:13], s[8:9], exec
	s_cselect_b32 s7, s11, s15
	s_cselect_b32 s49, s10, s14
	s_ashr_i32 s5, s4, 31
	s_lshl_b64 s[12:13], s[4:5], 19
	s_add_u32 s12, s25, s12
	s_addc_u32 s13, s26, s13
	s_and_b64 s[18:19], s[8:9], exec
	s_cselect_b32 s5, s13, s17
	s_cselect_b32 s50, s12, s16
	s_add_u32 s14, s14, 0x40080
	s_addc_u32 s15, s15, 0
	s_add_u32 s51, s16, 0x100
	v_mov_b32_e32 v0, 0
	s_addc_u32 s52, s17, 0
	s_mov_b32 s53, -2
	v_add_u32_e32 v254, 0x10000, v166
.Lup_peel:
	ds_read_b128 v[140:143], v254
	ds_read_b128 v[168:171], v254 offset:1024
	ds_read_b128 v[172:175], v254 offset:2048
	ds_read_b128 v[176:179], v254 offset:3072
	ds_read_b128 v[180:183], v254 offset:16384
	ds_read_b128 v[184:187], v254 offset:17408
	ds_read_b128 v[188:191], v254 offset:18432
	ds_read_b128 v[210:213], v254 offset:19456
	s_add_u32 s16, s14, 0xfffc0080
	s_addc_u32 s17, s15, -1
	s_cmp_eq_u32 s53, 12
	s_cselect_b32 s19, s7, s17
	s_cselect_b32 s18, s49, s16
	s_cselect_b32 s17, s5, s52
	s_cselect_b32 s16, s50, s51
	s_mov_b32 m0, s43
	ds_read_b128 v[214:217], v165
	ds_read_b128 v[218:221], v165 offset:1024
	ds_read_b128 v[222:225], v165 offset:2048
	ds_read_b128 v[226:229], v165 offset:3072
	ds_read_b128 v[230:233], v165 offset:4096
	ds_read_b128 v[234:237], v165 offset:5120
	ds_read_b128 v[238:241], v165 offset:6144
	ds_read_b128 v[242:245], v165 offset:7168
	global_load_lds_dwordx4 v136, s[14:15]
	s_mov_b32 m0, s44
	s_nop 0
	global_load_lds_dwordx4 v138, s[14:15]
	s_waitcnt vmcnt(8)
	s_waitcnt lgkmcnt(0)
	s_barrier
	s_setprio 1
	s_waitcnt lgkmcnt(0)
	v_mfma_f32_16x16x32_bf16 v[124:127], v[140:143], v[214:217], 0
	v_mfma_f32_16x16x32_bf16 v[116:119], v[172:175], v[214:217], 0
	v_mfma_f32_16x16x32_bf16 v[108:111], v[140:143], v[222:225], 0
	v_mfma_f32_16x16x32_bf16 v[100:103], v[172:175], v[222:225], 0
	v_mfma_f32_16x16x32_bf16 v[92:95], v[140:143], v[230:233], 0
	v_mfma_f32_16x16x32_bf16 v[84:87], v[172:175], v[230:233], 0
	v_mfma_f32_16x16x32_bf16 v[76:79], v[140:143], v[238:241], 0
	v_mfma_f32_16x16x32_bf16 v[68:71], v[172:175], v[238:241], 0
	v_mfma_f32_16x16x32_bf16 v[124:127], v[168:171], v[218:221], v[124:127]
	v_mfma_f32_16x16x32_bf16 v[116:119], v[176:179], v[218:221], v[116:119]
	v_mfma_f32_16x16x32_bf16 v[108:111], v[168:171], v[226:229], v[108:111]
	v_mfma_f32_16x16x32_bf16 v[100:103], v[176:179], v[226:229], v[100:103]
	v_mfma_f32_16x16x32_bf16 v[92:95], v[168:171], v[234:237], v[92:95]
	v_mfma_f32_16x16x32_bf16 v[84:87], v[176:179], v[234:237], v[84:87]
	v_mfma_f32_16x16x32_bf16 v[76:79], v[168:171], v[242:245], v[76:79]
	v_mfma_f32_16x16x32_bf16 v[68:71], v[176:179], v[242:245], v[68:71]
	s_setprio 0
	s_setprio 1
	v_mfma_f32_16x16x32_bf16 v[120:123], v[180:183], v[214:217], 0
	v_mfma_f32_16x16x32_bf16 v[112:115], v[188:191], v[214:217], 0
	v_mfma_f32_16x16x32_bf16 v[104:107], v[180:183], v[222:225], 0
	v_mfma_f32_16x16x32_bf16 v[96:99], v[188:191], v[222:225], 0
	v_mfma_f32_16x16x32_bf16 v[88:91], v[180:183], v[230:233], 0
	v_mfma_f32_16x16x32_bf16 v[80:83], v[188:191], v[230:233], 0
	v_mfma_f32_16x16x32_bf16 v[72:75], v[180:183], v[238:241], 0
	v_mfma_f32_16x16x32_bf16 v[64:67], v[188:191], v[238:241], 0
	v_mfma_f32_16x16x32_bf16 v[120:123], v[184:187], v[218:221], v[120:123]
	v_mfma_f32_16x16x32_bf16 v[112:115], v[210:213], v[218:221], v[112:115]
	v_mfma_f32_16x16x32_bf16 v[104:107], v[184:187], v[226:229], v[104:107]
	v_mfma_f32_16x16x32_bf16 v[96:99], v[210:213], v[226:229], v[96:99]
	v_mfma_f32_16x16x32_bf16 v[88:91], v[184:187], v[234:237], v[88:91]
	v_mfma_f32_16x16x32_bf16 v[80:83], v[210:213], v[234:237], v[80:83]
	v_mfma_f32_16x16x32_bf16 v[72:75], v[184:187], v[242:245], v[72:75]
	v_mfma_f32_16x16x32_bf16 v[64:67], v[210:213], v[242:245], v[64:67]
	s_setprio 0
	s_barrier
	s_mov_b32 m0, s27
	s_add_u32 s54, s16, 0x40000
	s_addc_u32 s55, s17, 0
	ds_read_b128 v[214:217], v165 offset:16384
	ds_read_b128 v[218:221], v165 offset:17408
	ds_read_b128 v[222:225], v165 offset:18432
	ds_read_b128 v[226:229], v165 offset:19456
	ds_read_b128 v[230:233], v165 offset:20480
	ds_read_b128 v[234:237], v165 offset:21504
	ds_read_b128 v[238:241], v165 offset:22528
	ds_read_b128 v[242:245], v165 offset:23552
	global_load_lds_dwordx4 v132, s[16:17]
	s_mov_b32 m0, s28
	s_nop 0
	global_load_lds_dwordx4 v128, s[16:17]
	s_mov_b32 m0, s29
	s_nop 0
	global_load_lds_dwordx4 v132, s[54:55]
	s_mov_b32 m0, s30
	s_nop 0
	global_load_lds_dwordx4 v128, s[54:55]
	s_mov_b32 m0, s22
	s_nop 0
	global_load_lds_dwordx4 v134, s[18:19]
	s_mov_b32 m0, s31
	s_nop 0
	global_load_lds_dwordx4 v130, s[18:19]
	s_waitcnt vmcnt(8)
	s_waitcnt lgkmcnt(0)
	s_barrier
; #define PG8_STAGE(bufoff, gbase, voff) do { _Pragma("unroll") for (int _i = 0; _i < 2; ++_i) \
;         __builtin_amdgcn_global_load_lds((const unsigned*)((const char*)(gbase) + (voff)[_i]), (PG8_LAS unsigned*)(lds + (bufoff) + ldsw + _i * 8192), 16, 0, 0); } while (0)
; #define PG8_LDA(dst, b, h) do { _Pragma("unroll") for (int m = 0; m < 4; ++m) _Pragma("unroll") for (int k = 0; k < 2; ++k) dst[m][k] = *(const PG8_LAS bf16x8*)(lds + PG8_SA(b, h) + aoff + m * 2048 + k * 1024); } while (0)
; #define PG8_LDB(dst, b, h) do { _Pragma("unroll") for (int n = 0; n < 2; ++n) _Pragma("unroll") for (int k = 0; k < 2; ++k) dst[n][k] = *(const PG8_LAS bf16x8*)(lds + PG8_SB(b, h) + boff + n * 2048 + k * 1024); } while (0)
; #define PG8_MMA(ai, bj, At, Bt) do { __builtin_amdgcn_s_setprio(1); _Pragma("unroll") for (int m = 0; m < 4; ++m) _Pragma("unroll") for (int n = 0; n < 2; ++n) _Pragma("unroll") for (int k = 0; k < 2; ++k) \
;         acc[ai][bj][m][n] = __builtin_amdgcn_mfma_f32_16x16x32_bf16(Bt[n][k], At[m][k], acc[ai][bj][m][n], 0, 0, 0); __builtin_amdgcn_s_setprio(0); } while (0)
; #define PG8_WAIT_V(n) asm volatile("s_waitcnt vmcnt(" #n ")" ::: "memory")
; #define PG8_WAIT_L(n) asm volatile("s_waitcnt lgkmcnt(" #n ")" ::: "memory")
; #define PG8_BAR __builtin_amdgcn_s_barrier()
; #define PG8_SCHED __builtin_amdgcn_sched_barrier(0)
; template <class Epi, class Sched, bool ALIGN_EPI = false, bool SP2 = false>
; __device__ __forceinline__ void gemm_phase(PG8_LAS unsigned char* lds, const Gemm g, const Sched& S, const Epi& E) {
;     ...
;             PG8_WAIT_V(8); PG8_WAIT_L(0); PG8_BAR; PG8_MMA(1, 0, At, B0); PG8_MMA(1, 1, At, B1); PG8_BAR; PG8_SCHED;
;             PG8_LDB(B0, 1, 0); PG8_LDB(B1, 1, 1); PG8_SCHED; PG8_LDA(At, 1, 0); PG8_STAGE(PG8_SA(0, 1), a2 + hstep, voffA);
;             PG8_WAIT_V(8); PG8_WAIT_L(0); PG8_BAR; PG8_MMA(0, 0, At, B0); PG8_MMA(0, 1, At, B1); PG8_BAR; PG8_SCHED;
	s_setprio 1
	s_waitcnt lgkmcnt(0)
	v_mfma_f32_16x16x32_bf16 v[60:63], v[140:143], v[214:217], 0
	v_mfma_f32_16x16x32_bf16 v[52:55], v[172:175], v[214:217], 0
	v_mfma_f32_16x16x32_bf16 v[44:47], v[140:143], v[222:225], 0
	v_mfma_f32_16x16x32_bf16 v[36:39], v[172:175], v[222:225], 0
	v_mfma_f32_16x16x32_bf16 v[28:31], v[140:143], v[230:233], 0
	v_mfma_f32_16x16x32_bf16 v[20:23], v[172:175], v[230:233], 0
	v_mfma_f32_16x16x32_bf16 v[12:15], v[140:143], v[238:241], 0
	v_mfma_f32_16x16x32_bf16 v[4:7], v[172:175], v[238:241], 0
	v_mfma_f32_16x16x32_bf16 v[60:63], v[168:171], v[218:221], v[60:63]
	v_mfma_f32_16x16x32_bf16 v[52:55], v[176:179], v[218:221], v[52:55]
	v_mfma_f32_16x16x32_bf16 v[44:47], v[168:171], v[226:229], v[44:47]
	v_mfma_f32_16x16x32_bf16 v[36:39], v[176:179], v[226:229], v[36:39]
	v_mfma_f32_16x16x32_bf16 v[28:31], v[168:171], v[234:237], v[28:31]
	v_mfma_f32_16x16x32_bf16 v[20:23], v[176:179], v[234:237], v[20:23]
	v_mfma_f32_16x16x32_bf16 v[12:15], v[168:171], v[242:245], v[12:15]
	v_mfma_f32_16x16x32_bf16 v[4:7], v[176:179], v[242:245], v[4:7]
	s_setprio 0
	s_setprio 1
	v_mfma_f32_16x16x32_bf16 v[56:59], v[180:183], v[214:217], 0
	v_mfma_f32_16x16x32_bf16 v[48:51], v[188:191], v[214:217], 0
	v_mfma_f32_16x16x32_bf16 v[40:43], v[180:183], v[222:225], 0
	v_mfma_f32_16x16x32_bf16 v[32:35], v[188:191], v[222:225], 0
	v_mfma_f32_16x16x32_bf16 v[24:27], v[180:183], v[230:233], 0
	v_mfma_f32_16x16x32_bf16 v[16:19], v[188:191], v[230:233], 0
	v_mfma_f32_16x16x32_bf16 v[8:11], v[180:183], v[238:241], 0
	v_mfma_f32_16x16x32_bf16 v[0:3], v[188:191], v[238:241], 0
	v_mfma_f32_16x16x32_bf16 v[56:59], v[184:187], v[218:221], v[56:59]
	v_mfma_f32_16x16x32_bf16 v[48:51], v[210:213], v[218:221], v[48:51]
	v_mfma_f32_16x16x32_bf16 v[40:43], v[184:187], v[226:229], v[40:43]
	v_mfma_f32_16x16x32_bf16 v[32:35], v[210:213], v[226:229], v[32:35]
	v_mfma_f32_16x16x32_bf16 v[24:27], v[184:187], v[234:237], v[24:27]
	v_mfma_f32_16x16x32_bf16 v[16:19], v[210:213], v[234:237], v[16:19]
	v_mfma_f32_16x16x32_bf16 v[8:11], v[184:187], v[242:245], v[8:11]
	v_mfma_f32_16x16x32_bf16 v[0:3], v[210:213], v[242:245], v[0:3]
	s_setprio 0
	s_barrier
	ds_read_b128 v[140:143], v254 offset:32768
	ds_read_b128 v[168:171], v254 offset:33792
	ds_read_b128 v[172:175], v254 offset:34816
	ds_read_b128 v[176:179], v254 offset:35840
	ds_read_b128 v[180:183], v254 offset:49152
	ds_read_b128 v[184:187], v254 offset:50176
	ds_read_b128 v[188:191], v254 offset:51200
	ds_read_b128 v[210:213], v254 offset:52224
	s_add_u32 s18, s18, 0x40000
	s_addc_u32 s19, s19, 0
	s_mov_b32 m0, s33
	ds_read_b128 v[214:217], v165 offset:32768
	ds_read_b128 v[218:221], v165 offset:33792
	ds_read_b128 v[222:225], v165 offset:34816
	ds_read_b128 v[226:229], v165 offset:35840
	ds_read_b128 v[230:233], v165 offset:36864
	ds_read_b128 v[234:237], v165 offset:37888
	ds_read_b128 v[238:241], v165 offset:38912
	ds_read_b128 v[242:245], v165 offset:39936
	global_load_lds_dwordx4 v134, s[18:19]
	s_mov_b32 m0, s34
	s_nop 0
	global_load_lds_dwordx4 v130, s[18:19]
	s_waitcnt vmcnt(8)
	s_waitcnt lgkmcnt(0)
	s_barrier
	s_setprio 1
	s_waitcnt lgkmcnt(0)
	v_mfma_f32_16x16x32_bf16 v[124:127], v[140:143], v[214:217], v[124:127]
	v_mfma_f32_16x16x32_bf16 v[116:119], v[172:175], v[214:217], v[116:119]
	v_mfma_f32_16x16x32_bf16 v[108:111], v[140:143], v[222:225], v[108:111]
	v_mfma_f32_16x16x32_bf16 v[100:103], v[172:175], v[222:225], v[100:103]
	v_mfma_f32_16x16x32_bf16 v[92:95], v[140:143], v[230:233], v[92:95]
	v_mfma_f32_16x16x32_bf16 v[84:87], v[172:175], v[230:233], v[84:87]
	v_mfma_f32_16x16x32_bf16 v[76:79], v[140:143], v[238:241], v[76:79]
	v_mfma_f32_16x16x32_bf16 v[68:71], v[172:175], v[238:241], v[68:71]
	v_mfma_f32_16x16x32_bf16 v[124:127], v[168:171], v[218:221], v[124:127]
	v_mfma_f32_16x16x32_bf16 v[116:119], v[176:179], v[218:221], v[116:119]
	v_mfma_f32_16x16x32_bf16 v[108:111], v[168:171], v[226:229], v[108:111]
	v_mfma_f32_16x16x32_bf16 v[100:103], v[176:179], v[226:229], v[100:103]
	v_mfma_f32_16x16x32_bf16 v[92:95], v[168:171], v[234:237], v[92:95]
	v_mfma_f32_16x16x32_bf16 v[84:87], v[176:179], v[234:237], v[84:87]
	v_mfma_f32_16x16x32_bf16 v[76:79], v[168:171], v[242:245], v[76:79]
	v_mfma_f32_16x16x32_bf16 v[68:71], v[176:179], v[242:245], v[68:71]
	s_setprio 0
	s_setprio 1
	v_mfma_f32_16x16x32_bf16 v[120:123], v[180:183], v[214:217], v[120:123]
	v_mfma_f32_16x16x32_bf16 v[112:115], v[188:191], v[214:217], v[112:115]
	v_mfma_f32_16x16x32_bf16 v[104:107], v[180:183], v[222:225], v[104:107]
	v_mfma_f32_16x16x32_bf16 v[96:99], v[188:191], v[222:225], v[96:99]
	v_mfma_f32_16x16x32_bf16 v[88:91], v[180:183], v[230:233], v[88:91]
	v_mfma_f32_16x16x32_bf16 v[80:83], v[188:191], v[230:233], v[80:83]
	v_mfma_f32_16x16x32_bf16 v[72:75], v[180:183], v[238:241], v[72:75]
	v_mfma_f32_16x16x32_bf16 v[64:67], v[188:191], v[238:241], v[64:67]
	v_mfma_f32_16x16x32_bf16 v[120:123], v[184:187], v[218:221], v[120:123]
	v_mfma_f32_16x16x32_bf16 v[112:115], v[210:213], v[218:221], v[112:115]
	v_mfma_f32_16x16x32_bf16 v[104:107], v[184:187], v[226:229], v[104:107]
	v_mfma_f32_16x16x32_bf16 v[96:99], v[210:213], v[226:229], v[96:99]
	v_mfma_f32_16x16x32_bf16 v[88:91], v[184:187], v[234:237], v[88:91]
	v_mfma_f32_16x16x32_bf16 v[80:83], v[210:213], v[234:237], v[80:83]
	v_mfma_f32_16x16x32_bf16 v[72:75], v[184:187], v[242:245], v[72:75]
	v_mfma_f32_16x16x32_bf16 v[64:67], v[210:213], v[242:245], v[64:67]
	s_setprio 0
	s_barrier
; #define PG8_STAGE(bufoff, gbase, voff) do { _Pragma("unroll") for (int _i = 0; _i < 2; ++_i) \
;         __builtin_amdgcn_global_load_lds((const unsigned*)((const char*)(gbase) + (voff)[_i]), (PG8_LAS unsigned*)(lds + (bufoff) + ldsw + _i * 8192), 16, 0, 0); } while (0)
; #define PG8_LDA(dst, b, h) do { _Pragma("unroll") for (int m = 0; m < 4; ++m) _Pragma("unroll") for (int k = 0; k < 2; ++k) dst[m][k] = *(const PG8_LAS bf16x8*)(lds + PG8_SA(b, h) + aoff + m * 2048 + k * 1024); } while (0)
; #define PG8_LDB(dst, b, h) do { _Pragma("unroll") for (int n = 0; n < 2; ++n) _Pragma("unroll") for (int k = 0; k < 2; ++k) dst[n][k] = *(const PG8_LAS bf16x8*)(lds + PG8_SB(b, h) + boff + n * 2048 + k * 1024); } while (0)
; #define PG8_MMA(ai, bj, At, Bt) do { __builtin_amdgcn_s_setprio(1); _Pragma("unroll") for (int m = 0; m < 4; ++m) _Pragma("unroll") for (int n = 0; n < 2; ++n) _Pragma("unroll") for (int k = 0; k < 2; ++k) \
;         acc[ai][bj][m][n] = __builtin_amdgcn_mfma_f32_16x16x32_bf16(Bt[n][k], At[m][k], acc[ai][bj][m][n], 0, 0, 0); __builtin_amdgcn_s_setprio(0); } while (0)
; #define PG8_WAIT_V(n) asm volatile("s_waitcnt vmcnt(" #n ")" ::: "memory")
; #define PG8_WAIT_L(n) asm volatile("s_waitcnt lgkmcnt(" #n ")" ::: "memory")
; #define PG8_BAR __builtin_amdgcn_s_barrier()
; #define PG8_SCHED __builtin_amdgcn_sched_barrier(0)
; template <class Epi, class Sched, bool ALIGN_EPI = false, bool SP2 = false>
; __device__ __forceinline__ void gemm_phase(PG8_LAS unsigned char* lds, const Gemm g, const Sched& S, const Epi& E) {
;     ...
;             PG8_LDB(B0, 0, 0); PG8_LDB(B1, 0, 1); PG8_SCHED; PG8_LDA(At, 0, 0); PG8_STAGE(PG8_SA(1, 1), a1 + hstep, voffA);
;             PG8_WAIT_V(8); PG8_WAIT_L(0); PG8_BAR; PG8_MMA(0, 0, At, B0); PG8_MMA(0, 1, At, B1); PG8_BAR; PG8_SCHED;
;             PG8_LDA(At, 0, 1); PG8_STAGE(PG8_SB(0, 0), b2, voffB); PG8_STAGE(PG8_SB(0, 1), b2 + hstep, voffB); PG8_STAGE(PG8_SA(0, 0), a2, voffA);
;     ...
;             PG8_LDA(At, 1, 1); PG8_STAGE(PG8_SB(1, 0), b3, voffB); PG8_STAGE(PG8_SB(1, 1), b3 + hstep, voffB); PG8_STAGE(PG8_SA(1, 0), a3, voffA);
;             PG8_WAIT_V(8); PG8_WAIT_L(0); PG8_BAR; PG8_MMA(1, 0, At, B0); PG8_MMA(1, 1, At, B1); PG8_BAR; PG8_SCHED;
	s_mov_b32 m0, s37
	s_add_u32 s16, s16, 0x40080
	s_addc_u32 s17, s17, 0
	ds_read_b128 v[214:217], v165 offset:49152
	ds_read_b128 v[218:221], v165 offset:50176
	ds_read_b128 v[222:225], v165 offset:51200
	ds_read_b128 v[226:229], v165 offset:52224
	ds_read_b128 v[230:233], v165 offset:53248
	ds_read_b128 v[234:237], v165 offset:54272
	ds_read_b128 v[238:241], v165 offset:55296
	ds_read_b128 v[242:245], v165 offset:56320
	s_add_u32 s98, s16, 0xfffc0000
	s_addc_u32 s99, s17, -1
	global_load_lds_dwordx4 v132, s[98:99]
	s_mov_b32 m0, s38
	s_nop 0
	global_load_lds_dwordx4 v128, s[98:99]
	s_mov_b32 m0, s41
	s_nop 0
	global_load_lds_dwordx4 v132, s[16:17]
	s_mov_b32 m0, s42
	s_nop 0
	global_load_lds_dwordx4 v128, s[16:17]
	s_mov_b32 m0, s39
	s_nop 0
	s_add_u32 s100, s18, 0xfffc0080
	s_addc_u32 s101, s19, -1
	global_load_lds_dwordx4 v134, s[100:101]
	s_mov_b32 m0, s40
	s_nop 0
	global_load_lds_dwordx4 v130, s[100:101]
	s_waitcnt vmcnt(8)
	s_waitcnt lgkmcnt(0)
	s_barrier
	s_setprio 1
	s_waitcnt lgkmcnt(0)
	v_mfma_f32_16x16x32_bf16 v[60:63], v[140:143], v[214:217], v[60:63]
	v_mfma_f32_16x16x32_bf16 v[52:55], v[172:175], v[214:217], v[52:55]
	v_mfma_f32_16x16x32_bf16 v[44:47], v[140:143], v[222:225], v[44:47]
	v_mfma_f32_16x16x32_bf16 v[36:39], v[172:175], v[222:225], v[36:39]
	v_mfma_f32_16x16x32_bf16 v[28:31], v[140:143], v[230:233], v[28:31]
	v_mfma_f32_16x16x32_bf16 v[20:23], v[172:175], v[230:233], v[20:23]
	v_mfma_f32_16x16x32_bf16 v[12:15], v[140:143], v[238:241], v[12:15]
	v_mfma_f32_16x16x32_bf16 v[4:7], v[172:175], v[238:241], v[4:7]
	v_mfma_f32_16x16x32_bf16 v[60:63], v[168:171], v[218:221], v[60:63]
	v_mfma_f32_16x16x32_bf16 v[52:55], v[176:179], v[218:221], v[52:55]
	v_mfma_f32_16x16x32_bf16 v[44:47], v[168:171], v[226:229], v[44:47]
	v_mfma_f32_16x16x32_bf16 v[36:39], v[176:179], v[226:229], v[36:39]
	v_mfma_f32_16x16x32_bf16 v[28:31], v[168:171], v[234:237], v[28:31]
	v_mfma_f32_16x16x32_bf16 v[20:23], v[176:179], v[234:237], v[20:23]
	v_mfma_f32_16x16x32_bf16 v[12:15], v[168:171], v[242:245], v[12:15]
	v_mfma_f32_16x16x32_bf16 v[4:7], v[176:179], v[242:245], v[4:7]
	s_setprio 0
	s_setprio 1
	v_mfma_f32_16x16x32_bf16 v[56:59], v[180:183], v[214:217], v[56:59]
	v_mfma_f32_16x16x32_bf16 v[48:51], v[188:191], v[214:217], v[48:51]
	v_mfma_f32_16x16x32_bf16 v[40:43], v[180:183], v[222:225], v[40:43]
	v_mfma_f32_16x16x32_bf16 v[32:35], v[188:191], v[222:225], v[32:35]
	v_mfma_f32_16x16x32_bf16 v[24:27], v[180:183], v[230:233], v[24:27]
	v_mfma_f32_16x16x32_bf16 v[16:19], v[188:191], v[230:233], v[16:19]
	v_mfma_f32_16x16x32_bf16 v[8:11], v[180:183], v[238:241], v[8:11]
	v_mfma_f32_16x16x32_bf16 v[0:3], v[188:191], v[238:241], v[0:3]
	v_mfma_f32_16x16x32_bf16 v[56:59], v[184:187], v[218:221], v[56:59]
	v_mfma_f32_16x16x32_bf16 v[48:51], v[210:213], v[218:221], v[48:51]
	v_mfma_f32_16x16x32_bf16 v[40:43], v[184:187], v[226:229], v[40:43]
	v_mfma_f32_16x16x32_bf16 v[32:35], v[210:213], v[226:229], v[32:35]
	v_mfma_f32_16x16x32_bf16 v[24:27], v[184:187], v[234:237], v[24:27]
	v_mfma_f32_16x16x32_bf16 v[16:19], v[210:213], v[234:237], v[16:19]
	v_mfma_f32_16x16x32_bf16 v[8:11], v[184:187], v[242:245], v[8:11]
	v_mfma_f32_16x16x32_bf16 v[0:3], v[210:213], v[242:245], v[0:3]
	s_setprio 0
	s_barrier
	s_add_i32 s53, s53, 2
	s_add_u32 s14, s14, 0x100
	s_addc_u32 s15, s15, 0
	s_add_u32 s51, s51, 0x100
	s_addc_u32 s52, s52, 0
	s_cmp_gt_u32 s53, 13
.LBB0_446:
	ds_read_b128 v[140:143], v254
	ds_read_b128 v[168:171], v254 offset:1024
	ds_read_b128 v[172:175], v254 offset:2048
	ds_read_b128 v[176:179], v254 offset:3072
	ds_read_b128 v[180:183], v254 offset:16384
	ds_read_b128 v[184:187], v254 offset:17408
	ds_read_b128 v[188:191], v254 offset:18432
	ds_read_b128 v[210:213], v254 offset:19456
	s_add_u32 s16, s14, 0xfffc0080
	s_addc_u32 s17, s15, -1
	s_cmp_eq_u32 s53, 12
	s_cselect_b32 s19, s7, s17
	s_cselect_b32 s18, s49, s16
	s_cselect_b32 s17, s5, s52
	s_cselect_b32 s16, s50, s51
	s_mov_b32 m0, s43
	ds_read_b128 v[214:217], v165
	ds_read_b128 v[218:221], v165 offset:1024
	ds_read_b128 v[222:225], v165 offset:2048
	ds_read_b128 v[226:229], v165 offset:3072
	ds_read_b128 v[230:233], v165 offset:4096
	ds_read_b128 v[234:237], v165 offset:5120
	ds_read_b128 v[238:241], v165 offset:6144
	ds_read_b128 v[242:245], v165 offset:7168
	global_load_lds_dwordx4 v136, s[14:15]
	s_mov_b32 m0, s44
	s_nop 0
	global_load_lds_dwordx4 v138, s[14:15]
	s_waitcnt vmcnt(8)
	s_waitcnt lgkmcnt(0)
	s_barrier
	s_setprio 1
	s_waitcnt lgkmcnt(0)
	v_mfma_f32_16x16x32_bf16 v[124:127], v[140:143], v[214:217], v[124:127]
	v_mfma_f32_16x16x32_bf16 v[116:119], v[172:175], v[214:217], v[116:119]
	v_mfma_f32_16x16x32_bf16 v[108:111], v[140:143], v[222:225], v[108:111]
	v_mfma_f32_16x16x32_bf16 v[100:103], v[172:175], v[222:225], v[100:103]
	v_mfma_f32_16x16x32_bf16 v[92:95], v[140:143], v[230:233], v[92:95]
	v_mfma_f32_16x16x32_bf16 v[84:87], v[172:175], v[230:233], v[84:87]
	v_mfma_f32_16x16x32_bf16 v[76:79], v[140:143], v[238:241], v[76:79]
	v_mfma_f32_16x16x32_bf16 v[68:71], v[172:175], v[238:241], v[68:71]
	v_mfma_f32_16x16x32_bf16 v[124:127], v[168:171], v[218:221], v[124:127]
	v_mfma_f32_16x16x32_bf16 v[116:119], v[176:179], v[218:221], v[116:119]
	v_mfma_f32_16x16x32_bf16 v[108:111], v[168:171], v[226:229], v[108:111]
	v_mfma_f32_16x16x32_bf16 v[100:103], v[176:179], v[226:229], v[100:103]
	v_mfma_f32_16x16x32_bf16 v[92:95], v[168:171], v[234:237], v[92:95]
	v_mfma_f32_16x16x32_bf16 v[84:87], v[176:179], v[234:237], v[84:87]
	v_mfma_f32_16x16x32_bf16 v[76:79], v[168:171], v[242:245], v[76:79]
	v_mfma_f32_16x16x32_bf16 v[68:71], v[176:179], v[242:245], v[68:71]
	s_setprio 0
	s_setprio 1
	v_mfma_f32_16x16x32_bf16 v[120:123], v[180:183], v[214:217], v[120:123]
	v_mfma_f32_16x16x32_bf16 v[112:115], v[188:191], v[214:217], v[112:115]
	v_mfma_f32_16x16x32_bf16 v[104:107], v[180:183], v[222:225], v[104:107]
	v_mfma_f32_16x16x32_bf16 v[96:99], v[188:191], v[222:225], v[96:99]
	v_mfma_f32_16x16x32_bf16 v[88:91], v[180:183], v[230:233], v[88:91]
	v_mfma_f32_16x16x32_bf16 v[80:83], v[188:191], v[230:233], v[80:83]
	v_mfma_f32_16x16x32_bf16 v[72:75], v[180:183], v[238:241], v[72:75]
	v_mfma_f32_16x16x32_bf16 v[64:67], v[188:191], v[238:241], v[64:67]
	v_mfma_f32_16x16x32_bf16 v[120:123], v[184:187], v[218:221], v[120:123]
	v_mfma_f32_16x16x32_bf16 v[112:115], v[210:213], v[218:221], v[112:115]
	v_mfma_f32_16x16x32_bf16 v[104:107], v[184:187], v[226:229], v[104:107]
	v_mfma_f32_16x16x32_bf16 v[96:99], v[210:213], v[226:229], v[96:99]
	v_mfma_f32_16x16x32_bf16 v[88:91], v[184:187], v[234:237], v[88:91]
	v_mfma_f32_16x16x32_bf16 v[80:83], v[210:213], v[234:237], v[80:83]
	v_mfma_f32_16x16x32_bf16 v[72:75], v[184:187], v[242:245], v[72:75]
	v_mfma_f32_16x16x32_bf16 v[64:67], v[210:213], v[242:245], v[64:67]
	s_setprio 0
	s_barrier
; #define PG8_STAGE(bufoff, gbase, voff) do { _Pragma("unroll") for (int _i = 0; _i < 2; ++_i) \
;         __builtin_amdgcn_global_load_lds((const unsigned*)((const char*)(gbase) + (voff)[_i]), (PG8_LAS unsigned*)(lds + (bufoff) + ldsw + _i * 8192), 16, 0, 0); } while (0)
; #define PG8_LDA(dst, b, h) do { _Pragma("unroll") for (int m = 0; m < 4; ++m) _Pragma("unroll") for (int k = 0; k < 2; ++k) dst[m][k] = *(const PG8_LAS bf16x8*)(lds + PG8_SA(b, h) + aoff + m * 2048 + k * 1024); } while (0)
; #define PG8_LDB(dst, b, h) do { _Pragma("unroll") for (int n = 0; n < 2; ++n) _Pragma("unroll") for (int k = 0; k < 2; ++k) dst[n][k] = *(const PG8_LAS bf16x8*)(lds + PG8_SB(b, h) + boff + n * 2048 + k * 1024); } while (0)
; #define PG8_MMA(ai, bj, At, Bt) do { __builtin_amdgcn_s_setprio(1); _Pragma("unroll") for (int m = 0; m < 4; ++m) _Pragma("unroll") for (int n = 0; n < 2; ++n) _Pragma("unroll") for (int k = 0; k < 2; ++k) \
;         acc[ai][bj][m][n] = __builtin_amdgcn_mfma_f32_16x16x32_bf16(Bt[n][k], At[m][k], acc[ai][bj][m][n], 0, 0, 0); __builtin_amdgcn_s_setprio(0); } while (0)
; #define PG8_WAIT_V(n) asm volatile("s_waitcnt vmcnt(" #n ")" ::: "memory")
; #define PG8_WAIT_L(n) asm volatile("s_waitcnt lgkmcnt(" #n ")" ::: "memory")
; #define PG8_BAR __builtin_amdgcn_s_barrier()
; #define PG8_SCHED __builtin_amdgcn_sched_barrier(0)
; template <class Epi, class Sched, bool ALIGN_EPI = false, bool SP2 = false>
; __device__ __forceinline__ void gemm_phase(PG8_LAS unsigned char* lds, const Gemm g, const Sched& S, const Epi& E) {
;     ...
;             PG8_WAIT_V(8); PG8_WAIT_L(0); PG8_BAR; PG8_MMA(0, 0, At, B0); PG8_MMA(0, 1, At, B1); PG8_BAR; PG8_SCHED;
;             PG8_LDA(At, 0, 1); PG8_STAGE(PG8_SB(0, 0), b2, voffB); PG8_STAGE(PG8_SB(0, 1), b2 + hstep, voffB); PG8_STAGE(PG8_SA(0, 0), a2, voffA);
;             PG8_WAIT_V(8); PG8_WAIT_L(0); PG8_BAR; PG8_MMA(1, 0, At, B0); PG8_MMA(1, 1, At, B1); PG8_BAR; PG8_SCHED;
;             PG8_LDB(B0, 1, 0); PG8_LDB(B1, 1, 1); PG8_SCHED; PG8_LDA(At, 1, 0); PG8_STAGE(PG8_SA(0, 1), a2 + hstep, voffA);
;             PG8_WAIT_V(8); PG8_WAIT_L(0); PG8_BAR; PG8_MMA(0, 0, At, B0); PG8_MMA(0, 1, At, B1); PG8_BAR; PG8_SCHED;
	s_mov_b32 m0, s27
	s_add_u32 s54, s16, 0x40000
	s_addc_u32 s55, s17, 0
	ds_read_b128 v[214:217], v165 offset:16384
	ds_read_b128 v[218:221], v165 offset:17408
	ds_read_b128 v[222:225], v165 offset:18432
	ds_read_b128 v[226:229], v165 offset:19456
	ds_read_b128 v[230:233], v165 offset:20480
	ds_read_b128 v[234:237], v165 offset:21504
	ds_read_b128 v[238:241], v165 offset:22528
	ds_read_b128 v[242:245], v165 offset:23552
	global_load_lds_dwordx4 v132, s[16:17]
	s_mov_b32 m0, s28
	s_nop 0
	global_load_lds_dwordx4 v128, s[16:17]
	s_mov_b32 m0, s29
	s_nop 0
	global_load_lds_dwordx4 v132, s[54:55]
	s_mov_b32 m0, s30
	s_nop 0
	global_load_lds_dwordx4 v128, s[54:55]
	s_mov_b32 m0, s22
	s_nop 0
	global_load_lds_dwordx4 v134, s[18:19]
	s_mov_b32 m0, s31
	s_nop 0
	global_load_lds_dwordx4 v130, s[18:19]
	s_waitcnt vmcnt(8)
	s_waitcnt lgkmcnt(0)
	s_barrier
	s_setprio 1
	s_waitcnt lgkmcnt(0)
	v_mfma_f32_16x16x32_bf16 v[60:63], v[140:143], v[214:217], v[60:63]
	v_mfma_f32_16x16x32_bf16 v[52:55], v[172:175], v[214:217], v[52:55]
	v_mfma_f32_16x16x32_bf16 v[44:47], v[140:143], v[222:225], v[44:47]
	v_mfma_f32_16x16x32_bf16 v[36:39], v[172:175], v[222:225], v[36:39]
	v_mfma_f32_16x16x32_bf16 v[28:31], v[140:143], v[230:233], v[28:31]
	v_mfma_f32_16x16x32_bf16 v[20:23], v[172:175], v[230:233], v[20:23]
	v_mfma_f32_16x16x32_bf16 v[12:15], v[140:143], v[238:241], v[12:15]
	v_mfma_f32_16x16x32_bf16 v[4:7], v[172:175], v[238:241], v[4:7]
	v_mfma_f32_16x16x32_bf16 v[60:63], v[168:171], v[218:221], v[60:63]
	v_mfma_f32_16x16x32_bf16 v[52:55], v[176:179], v[218:221], v[52:55]
	v_mfma_f32_16x16x32_bf16 v[44:47], v[168:171], v[226:229], v[44:47]
	v_mfma_f32_16x16x32_bf16 v[36:39], v[176:179], v[226:229], v[36:39]
	v_mfma_f32_16x16x32_bf16 v[28:31], v[168:171], v[234:237], v[28:31]
	v_mfma_f32_16x16x32_bf16 v[20:23], v[176:179], v[234:237], v[20:23]
	v_mfma_f32_16x16x32_bf16 v[12:15], v[168:171], v[242:245], v[12:15]
	v_mfma_f32_16x16x32_bf16 v[4:7], v[176:179], v[242:245], v[4:7]
	s_setprio 0
	s_setprio 1
	v_mfma_f32_16x16x32_bf16 v[56:59], v[180:183], v[214:217], v[56:59]
	v_mfma_f32_16x16x32_bf16 v[48:51], v[188:191], v[214:217], v[48:51]
	v_mfma_f32_16x16x32_bf16 v[40:43], v[180:183], v[222:225], v[40:43]
	v_mfma_f32_16x16x32_bf16 v[32:35], v[188:191], v[222:225], v[32:35]
	v_mfma_f32_16x16x32_bf16 v[24:27], v[180:183], v[230:233], v[24:27]
	v_mfma_f32_16x16x32_bf16 v[16:19], v[188:191], v[230:233], v[16:19]
	v_mfma_f32_16x16x32_bf16 v[8:11], v[180:183], v[238:241], v[8:11]
	v_mfma_f32_16x16x32_bf16 v[0:3], v[188:191], v[238:241], v[0:3]
	v_mfma_f32_16x16x32_bf16 v[56:59], v[184:187], v[218:221], v[56:59]
	v_mfma_f32_16x16x32_bf16 v[48:51], v[210:213], v[218:221], v[48:51]
	v_mfma_f32_16x16x32_bf16 v[40:43], v[184:187], v[226:229], v[40:43]
	v_mfma_f32_16x16x32_bf16 v[32:35], v[210:213], v[226:229], v[32:35]
	v_mfma_f32_16x16x32_bf16 v[24:27], v[184:187], v[234:237], v[24:27]
	v_mfma_f32_16x16x32_bf16 v[16:19], v[210:213], v[234:237], v[16:19]
	v_mfma_f32_16x16x32_bf16 v[8:11], v[184:187], v[242:245], v[8:11]
	v_mfma_f32_16x16x32_bf16 v[0:3], v[210:213], v[242:245], v[0:3]
	s_setprio 0
	s_barrier
	ds_read_b128 v[140:143], v254 offset:32768
	ds_read_b128 v[168:171], v254 offset:33792
	ds_read_b128 v[172:175], v254 offset:34816
	ds_read_b128 v[176:179], v254 offset:35840
	ds_read_b128 v[180:183], v254 offset:49152
	ds_read_b128 v[184:187], v254 offset:50176
	ds_read_b128 v[188:191], v254 offset:51200
	ds_read_b128 v[210:213], v254 offset:52224
	s_add_u32 s18, s18, 0x40000
	s_addc_u32 s19, s19, 0
	s_mov_b32 m0, s33
	ds_read_b128 v[214:217], v165 offset:32768
	ds_read_b128 v[218:221], v165 offset:33792
	ds_read_b128 v[222:225], v165 offset:34816
	ds_read_b128 v[226:229], v165 offset:35840
	ds_read_b128 v[230:233], v165 offset:36864
	ds_read_b128 v[234:237], v165 offset:37888
	ds_read_b128 v[238:241], v165 offset:38912
	ds_read_b128 v[242:245], v165 offset:39936
	global_load_lds_dwordx4 v134, s[18:19]
	s_mov_b32 m0, s34
	s_nop 0
	global_load_lds_dwordx4 v130, s[18:19]
	s_waitcnt vmcnt(8)
	s_waitcnt lgkmcnt(0)
	s_barrier
; #define PG8_STAGE(bufoff, gbase, voff) do { _Pragma("unroll") for (int _i = 0; _i < 2; ++_i) \
;         __builtin_amdgcn_global_load_lds((const unsigned*)((const char*)(gbase) + (voff)[_i]), (PG8_LAS unsigned*)(lds + (bufoff) + ldsw + _i * 8192), 16, 0, 0); } while (0)
; #define PG8_LDA(dst, b, h) do { _Pragma("unroll") for (int m = 0; m < 4; ++m) _Pragma("unroll") for (int k = 0; k < 2; ++k) dst[m][k] = *(const PG8_LAS bf16x8*)(lds + PG8_SA(b, h) + aoff + m * 2048 + k * 1024); } while (0)
; #define PG8_LDB(dst, b, h) do { _Pragma("unroll") for (int n = 0; n < 2; ++n) _Pragma("unroll") for (int k = 0; k < 2; ++k) dst[n][k] = *(const PG8_LAS bf16x8*)(lds + PG8_SB(b, h) + boff + n * 2048 + k * 1024); } while (0)
; #define PG8_MMA(ai, bj, At, Bt) do { __builtin_amdgcn_s_setprio(1); _Pragma("unroll") for (int m = 0; m < 4; ++m) _Pragma("unroll") for (int n = 0; n < 2; ++n) _Pragma("unroll") for (int k = 0; k < 2; ++k) \
;         acc[ai][bj][m][n] = __builtin_amdgcn_mfma_f32_16x16x32_bf16(Bt[n][k], At[m][k], acc[ai][bj][m][n], 0, 0, 0); __builtin_amdgcn_s_setprio(0); } while (0)
; #define PG8_WAIT_V(n) asm volatile("s_waitcnt vmcnt(" #n ")" ::: "memory")
; #define PG8_WAIT_L(n) asm volatile("s_waitcnt lgkmcnt(" #n ")" ::: "memory")
; template <class Epi, class Sched, bool ALIGN_EPI = false, bool SP2 = false>
; __device__ __forceinline__ void gemm_phase(PG8_LAS unsigned char* lds, const Gemm g, const Sched& S, const Epi& E) {
;     ...
;         for (int t = 0; t < nt; t += 2) {
;             const bool last = (t == nt - 2);
;             const char* a1 = cA + (size_t)(t + 1) * kstep;
;             const char* a2 = last ? nA : cA + (size_t)(t + 2) * kstep; const char* b2 = last ? nB : cB + (size_t)(t + 2) * kstep;
;             const char* a3 = a2 + kstep; const char* b3 = b2 + kstep;
;             if (last && has_next) S.a_ready(nxt);
;     ...
;             PG8_LDB(B0, 1, 0); PG8_LDB(B1, 1, 1); PG8_SCHED; PG8_LDA(At, 1, 0); PG8_STAGE(PG8_SA(0, 1), a2 + hstep, voffA);
;             PG8_WAIT_V(8); PG8_WAIT_L(0); PG8_BAR; PG8_MMA(0, 0, At, B0); PG8_MMA(0, 1, At, B1); PG8_BAR; PG8_SCHED;
;             PG8_LDA(At, 1, 1); PG8_STAGE(PG8_SB(1, 0), b3, voffB); PG8_STAGE(PG8_SB(1, 1), b3 + hstep, voffB); PG8_STAGE(PG8_SA(1, 0), a3, voffA);
;             PG8_WAIT_V(8); PG8_WAIT_L(0); PG8_BAR; PG8_MMA(1, 0, At, B0); PG8_MMA(1, 1, At, B1); PG8_BAR; PG8_SCHED;
	s_setprio 1
	s_waitcnt lgkmcnt(0)
	v_mfma_f32_16x16x32_bf16 v[124:127], v[140:143], v[214:217], v[124:127]
	v_mfma_f32_16x16x32_bf16 v[116:119], v[172:175], v[214:217], v[116:119]
	v_mfma_f32_16x16x32_bf16 v[108:111], v[140:143], v[222:225], v[108:111]
	v_mfma_f32_16x16x32_bf16 v[100:103], v[172:175], v[222:225], v[100:103]
	v_mfma_f32_16x16x32_bf16 v[92:95], v[140:143], v[230:233], v[92:95]
	v_mfma_f32_16x16x32_bf16 v[84:87], v[172:175], v[230:233], v[84:87]
	v_mfma_f32_16x16x32_bf16 v[76:79], v[140:143], v[238:241], v[76:79]
	v_mfma_f32_16x16x32_bf16 v[68:71], v[172:175], v[238:241], v[68:71]
	v_mfma_f32_16x16x32_bf16 v[124:127], v[168:171], v[218:221], v[124:127]
	v_mfma_f32_16x16x32_bf16 v[116:119], v[176:179], v[218:221], v[116:119]
	v_mfma_f32_16x16x32_bf16 v[108:111], v[168:171], v[226:229], v[108:111]
	v_mfma_f32_16x16x32_bf16 v[100:103], v[176:179], v[226:229], v[100:103]
	v_mfma_f32_16x16x32_bf16 v[92:95], v[168:171], v[234:237], v[92:95]
	v_mfma_f32_16x16x32_bf16 v[84:87], v[176:179], v[234:237], v[84:87]
	v_mfma_f32_16x16x32_bf16 v[76:79], v[168:171], v[242:245], v[76:79]
	v_mfma_f32_16x16x32_bf16 v[68:71], v[176:179], v[242:245], v[68:71]
	s_setprio 0
	s_setprio 1
	v_mfma_f32_16x16x32_bf16 v[120:123], v[180:183], v[214:217], v[120:123]
	v_mfma_f32_16x16x32_bf16 v[112:115], v[188:191], v[214:217], v[112:115]
	v_mfma_f32_16x16x32_bf16 v[104:107], v[180:183], v[222:225], v[104:107]
	v_mfma_f32_16x16x32_bf16 v[96:99], v[188:191], v[222:225], v[96:99]
	v_mfma_f32_16x16x32_bf16 v[88:91], v[180:183], v[230:233], v[88:91]
	v_mfma_f32_16x16x32_bf16 v[80:83], v[188:191], v[230:233], v[80:83]
	v_mfma_f32_16x16x32_bf16 v[72:75], v[180:183], v[238:241], v[72:75]
	v_mfma_f32_16x16x32_bf16 v[64:67], v[188:191], v[238:241], v[64:67]
	v_mfma_f32_16x16x32_bf16 v[120:123], v[184:187], v[218:221], v[120:123]
	v_mfma_f32_16x16x32_bf16 v[112:115], v[210:213], v[218:221], v[112:115]
	v_mfma_f32_16x16x32_bf16 v[104:107], v[184:187], v[226:229], v[104:107]
	v_mfma_f32_16x16x32_bf16 v[96:99], v[210:213], v[226:229], v[96:99]
	v_mfma_f32_16x16x32_bf16 v[88:91], v[184:187], v[234:237], v[88:91]
	v_mfma_f32_16x16x32_bf16 v[80:83], v[210:213], v[234:237], v[80:83]
	v_mfma_f32_16x16x32_bf16 v[72:75], v[184:187], v[242:245], v[72:75]
	v_mfma_f32_16x16x32_bf16 v[64:67], v[210:213], v[242:245], v[64:67]
	s_setprio 0
	s_barrier
	s_mov_b32 m0, s37
	s_add_u32 s16, s16, 0x40080
	s_addc_u32 s17, s17, 0
	ds_read_b128 v[214:217], v165 offset:49152
	ds_read_b128 v[218:221], v165 offset:50176
	ds_read_b128 v[222:225], v165 offset:51200
	ds_read_b128 v[226:229], v165 offset:52224
	ds_read_b128 v[230:233], v165 offset:53248
	ds_read_b128 v[234:237], v165 offset:54272
	ds_read_b128 v[238:241], v165 offset:55296
	ds_read_b128 v[242:245], v165 offset:56320
	s_add_u32 s98, s16, 0xfffc0000
	s_addc_u32 s99, s17, -1
	global_load_lds_dwordx4 v132, s[98:99]
	s_mov_b32 m0, s38
	s_nop 0
	global_load_lds_dwordx4 v128, s[98:99]
	s_mov_b32 m0, s41
	s_nop 0
	global_load_lds_dwordx4 v132, s[16:17]
	s_mov_b32 m0, s42
	s_nop 0
	global_load_lds_dwordx4 v128, s[16:17]
	s_mov_b32 m0, s39
	s_nop 0
	s_add_u32 s100, s18, 0xfffc0080
	s_addc_u32 s101, s19, -1
	global_load_lds_dwordx4 v134, s[100:101]
	s_mov_b32 m0, s40
	s_nop 0
	global_load_lds_dwordx4 v130, s[100:101]
	s_waitcnt vmcnt(8)
	s_waitcnt lgkmcnt(0)
	s_barrier
	s_setprio 1
	s_waitcnt lgkmcnt(0)
	v_mfma_f32_16x16x32_bf16 v[60:63], v[140:143], v[214:217], v[60:63]
	v_mfma_f32_16x16x32_bf16 v[52:55], v[172:175], v[214:217], v[52:55]
	v_mfma_f32_16x16x32_bf16 v[44:47], v[140:143], v[222:225], v[44:47]
	v_mfma_f32_16x16x32_bf16 v[36:39], v[172:175], v[222:225], v[36:39]
	v_mfma_f32_16x16x32_bf16 v[28:31], v[140:143], v[230:233], v[28:31]
	v_mfma_f32_16x16x32_bf16 v[20:23], v[172:175], v[230:233], v[20:23]
	v_mfma_f32_16x16x32_bf16 v[12:15], v[140:143], v[238:241], v[12:15]
	v_mfma_f32_16x16x32_bf16 v[4:7], v[172:175], v[238:241], v[4:7]
	v_mfma_f32_16x16x32_bf16 v[60:63], v[168:171], v[218:221], v[60:63]
	v_mfma_f32_16x16x32_bf16 v[52:55], v[176:179], v[218:221], v[52:55]
	v_mfma_f32_16x16x32_bf16 v[44:47], v[168:171], v[226:229], v[44:47]
	v_mfma_f32_16x16x32_bf16 v[36:39], v[176:179], v[226:229], v[36:39]
	v_mfma_f32_16x16x32_bf16 v[28:31], v[168:171], v[234:237], v[28:31]
	v_mfma_f32_16x16x32_bf16 v[20:23], v[176:179], v[234:237], v[20:23]
	v_mfma_f32_16x16x32_bf16 v[12:15], v[168:171], v[242:245], v[12:15]
	v_mfma_f32_16x16x32_bf16 v[4:7], v[176:179], v[242:245], v[4:7]
	s_setprio 0
	s_setprio 1
	v_mfma_f32_16x16x32_bf16 v[56:59], v[180:183], v[214:217], v[56:59]
	v_mfma_f32_16x16x32_bf16 v[48:51], v[188:191], v[214:217], v[48:51]
	v_mfma_f32_16x16x32_bf16 v[40:43], v[180:183], v[222:225], v[40:43]
	v_mfma_f32_16x16x32_bf16 v[32:35], v[188:191], v[222:225], v[32:35]
	v_mfma_f32_16x16x32_bf16 v[24:27], v[180:183], v[230:233], v[24:27]
	v_mfma_f32_16x16x32_bf16 v[16:19], v[188:191], v[230:233], v[16:19]
	v_mfma_f32_16x16x32_bf16 v[8:11], v[180:183], v[238:241], v[8:11]
	v_mfma_f32_16x16x32_bf16 v[0:3], v[188:191], v[238:241], v[0:3]
	v_mfma_f32_16x16x32_bf16 v[56:59], v[184:187], v[218:221], v[56:59]
	v_mfma_f32_16x16x32_bf16 v[48:51], v[210:213], v[218:221], v[48:51]
	v_mfma_f32_16x16x32_bf16 v[40:43], v[184:187], v[226:229], v[40:43]
	v_mfma_f32_16x16x32_bf16 v[32:35], v[210:213], v[226:229], v[32:35]
	v_mfma_f32_16x16x32_bf16 v[24:27], v[184:187], v[234:237], v[24:27]
	v_mfma_f32_16x16x32_bf16 v[16:19], v[210:213], v[234:237], v[16:19]
	v_mfma_f32_16x16x32_bf16 v[8:11], v[184:187], v[242:245], v[8:11]
	v_mfma_f32_16x16x32_bf16 v[0:3], v[210:213], v[242:245], v[0:3]
	s_setprio 0
	s_barrier
	s_add_i32 s53, s53, 2
	s_add_u32 s14, s14, 0x100
	s_addc_u32 s15, s15, 0
	s_add_u32 s51, s51, 0x100
	s_addc_u32 s52, s52, 0
	s_cmp_gt_u32 s53, 13
	s_cbranch_scc0 .LBB0_446
	s_and_b64 vcc, exec, s[2:3]
	s_cbranch_vccz .LBB0_449
	s_barrier
